# K-loop: formal DMA waits of the first K-tile skipped after an epilogue (P6, gate phases) so MFMAs start while epilogue stores drain
# baseline (speedup 1.0000x reference)
.LBB0_469:
	s_add_u32 s35, s65, 0x6400
	s_addc_u32 s84, s94, 0
	v_lshrrev_b32_e32 v16, 1, v10
	s_add_u32 s8, s0, 0x1000
	v_and_b32_e32 v16, 24, v16
	v_readlane_b32 s20, v254, 21
	s_addc_u32 s9, s1, 0
	v_and_b32_e32 v11, 15, v10
	v_lshlrev_b32_e32 v17, 1, v16
	v_lshlrev_b32_e32 v10, 2, v10
	s_lshl_b32 s3, s3, 5
	v_mov_b32_e32 v133, v161
	v_readlane_b32 s21, v254, 22
	v_lshl_or_b32 v166, s4, 6, v11
	v_lshl_or_b32 v11, v11, 6, v17
	s_lshl_b32 s4, s4, 13
	v_and_b32_e32 v10, 32, v10
	s_and_b32 s3, s3, 0x60
	s_add_i32 m0, s29, 0x18000
	v_lshl_add_u64 v[0:1], v[0:1], 0, s[38:39]
	v_lshl_add_u64 v[12:13], s[20:21], 0, v[132:133]
	v_mov_b32_e32 v131, v161
	v_bitop3_b32 v17, v11, s4, v10 bitop3:0xde
	s_lshl_b32 s4, s3, 7
	global_load_lds_dwordx4 v[0:1], off
	v_lshl_add_u64 v[0:1], v[2:3], 0, s[38:39]
	s_add_i32 m0, s29, 0x1a000
	s_add_i32 s85, s29, 0x8000
	s_add_i32 s86, s29, 0xa000
	v_lshl_add_u64 v[14:15], s[20:21], 0, v[130:131]
	v_bitop3_b32 v167, v11, s4, v10 bitop3:0xde
	global_load_lds_dwordx4 v[0:1], off
	v_lshl_add_u64 v[0:1], v[12:13], 0, s[38:39]
	s_mov_b32 m0, s85
	s_add_u32 s4, s22, 0x40080
	global_load_lds_dwordx4 v[0:1], off
	v_lshl_add_u64 v[0:1], v[14:15], 0, s[38:39]
	s_mov_b32 m0, s86
	s_addc_u32 s5, s23, 0
	global_load_lds_dwordx4 v[0:1], off
	s_add_i32 m0, s29, 0x1c000
	v_lshl_add_u64 v[0:1], s[4:5], 0, v[160:161]
	global_load_lds_dwordx4 v[0:1], off
	v_lshl_add_u64 v[0:1], s[4:5], 0, v[128:129]
	s_add_i32 m0, s29, 0x1e000
	s_cmpk_lt_u32 s2, 0x100
	global_load_lds_dwordx4 v[0:1], off
	s_waitcnt vmcnt(8)
	s_barrier
	v_lshlrev_b32_e32 v0, 14, v8
	v_and_b32_e32 v0, 0xffff8000, v0
	v_lshl_add_u32 v0, v7, 11, v0
	v_and_b32_e32 v1, 1, v8
	v_lshl_or_b32 v0, v1, 6, v0
	v_lshl_add_u32 v134, v9, 1, v0
	v_lshlrev_b32_e32 v0, 14, v4
	v_and_b32_e32 v0, 0xffff8000, v0
	s_waitcnt vmcnt(6)
	v_lshl_add_u32 v0, v5, 11, v0
	v_and_b32_e32 v1, 1, v4
	v_lshl_or_b32 v0, v1, 6, v0
	v_readlane_b32 s4, v254, 58
	s_cselect_b64 s[10:11], -1, 0
	v_or_b32_e32 v168, s3, v16
	v_mov_b32_e32 v135, v161
	v_lshl_add_u32 v136, v6, 1, v0
	v_mov_b32_e32 v137, v161
	s_mov_b32 s88, 0
	v_add_u32_e32 v169, 0, v17
	v_readlane_b32 s3, v254, 18
	s_mov_b32 s2, s4
	s_barrier
	v_readlane_b32 s5, v254, 59
	s_mov_b32 s99, 0
	s_branch .LBB0_472

.LBB0_471:
	s_mov_b32 s99, 1
	s_andn2_b64 vcc, exec, s[20:21]
	s_mov_b32 s3, s12
	s_mov_b32 s2, s14
	s_mov_b64 s[22:23], s[18:19]
	s_mov_b64 s[20:21], s[16:17]
	s_cbranch_vccz .LBB0_485

.LBB0_479:
	s_add_u32 s22, s20, 0xfffc0080
	s_addc_u32 s23, s21, -1
	s_add_i32 s78, 0, 0x10000
	s_cmp_eq_u32 s90, 12
	s_cselect_b32 s25, s15, s23
	s_cselect_b32 s24, s56, s22
	s_cselect_b32 s23, s13, s96
	s_cselect_b32 s22, s89, s95
	s_add_i32 s79, 0, 0x14000
	v_add_u32_e32 v150, s78, v167
	v_add_u32_e32 v158, s79, v167
	ds_read_b128 v[138:141], v150
	ds_read_b128 v[142:145], v150 offset:1024
	ds_read_b128 v[146:149], v150 offset:2048
	ds_read_b128 v[150:153], v150 offset:3072
	ds_read_b128 v[154:157], v158
	ds_read_b128 v[170:173], v158 offset:1024
	ds_read_b128 v[174:177], v158 offset:2048
	ds_read_b128 v[178:181], v158 offset:3072
	v_lshl_add_u64 v[158:159], s[20:21], 0, v[134:135]
	s_add_i32 m0, s29, 0xc000
	ds_read_b128 v[182:185], v169
	ds_read_b128 v[186:189], v169 offset:1024
	ds_read_b128 v[190:193], v169 offset:2048
	ds_read_b128 v[194:197], v169 offset:3072
	ds_read_b128 v[198:201], v169 offset:4096
	ds_read_b128 v[208:211], v169 offset:5120
	ds_read_b128 v[212:215], v169 offset:6144
	ds_read_b128 v[216:219], v169 offset:7168
	global_load_lds_dwordx4 v[158:159], off
	v_lshl_add_u64 v[158:159], s[20:21], 0, v[136:137]
	s_add_i32 m0, s29, 0xe000
	s_nop 0
	global_load_lds_dwordx4 v[158:159], off
	s_cmp_eq_u32 s99, 1
	s_cbranch_scc1 .Lskipw_p4a_0
	s_waitcnt vmcnt(8)
.Lskipw_p4a_0:
	s_waitcnt lgkmcnt(0)
	s_barrier
	s_setprio 1
	s_waitcnt lgkmcnt(0)
	v_mfma_f32_16x16x32_bf16 v[124:127], v[138:141], v[182:185], v[124:127]
	v_mfma_f32_16x16x32_bf16 v[120:123], v[146:149], v[182:185], v[120:123]
	v_mfma_f32_16x16x32_bf16 v[108:111], v[138:141], v[190:193], v[108:111]
	v_mfma_f32_16x16x32_bf16 v[104:107], v[146:149], v[190:193], v[104:107]
	v_mfma_f32_16x16x32_bf16 v[92:95], v[138:141], v[198:201], v[92:95]
	v_mfma_f32_16x16x32_bf16 v[88:91], v[146:149], v[198:201], v[88:91]
	v_mfma_f32_16x16x32_bf16 v[76:79], v[138:141], v[212:215], v[76:79]
	v_mfma_f32_16x16x32_bf16 v[72:75], v[146:149], v[212:215], v[72:75]
	v_mfma_f32_16x16x32_bf16 v[124:127], v[142:145], v[186:189], v[124:127]
	v_mfma_f32_16x16x32_bf16 v[120:123], v[150:153], v[186:189], v[120:123]
	v_mfma_f32_16x16x32_bf16 v[108:111], v[142:145], v[194:197], v[108:111]
	v_mfma_f32_16x16x32_bf16 v[104:107], v[150:153], v[194:197], v[104:107]
	v_mfma_f32_16x16x32_bf16 v[92:95], v[142:145], v[208:211], v[92:95]
	v_mfma_f32_16x16x32_bf16 v[88:91], v[150:153], v[208:211], v[88:91]
	v_mfma_f32_16x16x32_bf16 v[76:79], v[142:145], v[216:219], v[76:79]
	v_mfma_f32_16x16x32_bf16 v[72:75], v[150:153], v[216:219], v[72:75]
	s_setprio 0
	s_setprio 1
	v_mfma_f32_16x16x32_bf16 v[116:119], v[154:157], v[182:185], v[116:119]
	v_mfma_f32_16x16x32_bf16 v[112:115], v[174:177], v[182:185], v[112:115]
	v_mfma_f32_16x16x32_bf16 v[100:103], v[154:157], v[190:193], v[100:103]
	v_mfma_f32_16x16x32_bf16 v[96:99], v[174:177], v[190:193], v[96:99]
	v_mfma_f32_16x16x32_bf16 v[84:87], v[154:157], v[198:201], v[84:87]
	v_mfma_f32_16x16x32_bf16 v[80:83], v[174:177], v[198:201], v[80:83]
	v_mfma_f32_16x16x32_bf16 v[68:71], v[154:157], v[212:215], v[68:71]
	v_mfma_f32_16x16x32_bf16 v[64:67], v[174:177], v[212:215], v[64:67]
	v_mfma_f32_16x16x32_bf16 v[116:119], v[170:173], v[186:189], v[116:119]
	v_mfma_f32_16x16x32_bf16 v[112:115], v[178:181], v[186:189], v[112:115]
	v_mfma_f32_16x16x32_bf16 v[100:103], v[170:173], v[194:197], v[100:103]
	v_mfma_f32_16x16x32_bf16 v[96:99], v[178:181], v[194:197], v[96:99]
	v_mfma_f32_16x16x32_bf16 v[84:87], v[170:173], v[208:211], v[84:87]
	v_mfma_f32_16x16x32_bf16 v[80:83], v[178:181], v[208:211], v[80:83]
	v_mfma_f32_16x16x32_bf16 v[68:71], v[170:173], v[216:219], v[68:71]
	v_mfma_f32_16x16x32_bf16 v[64:67], v[178:181], v[216:219], v[64:67]
	s_setprio 0
	s_barrier
	s_add_i32 s78, s78, s28
	v_lshl_add_u64 v[158:159], s[22:23], 0, v[160:161]
	s_mov_b32 m0, s78
	ds_read_b128 v[182:185], v169 offset:16384
	ds_read_b128 v[186:189], v169 offset:17408
	ds_read_b128 v[190:193], v169 offset:18432
	ds_read_b128 v[194:197], v169 offset:19456
	ds_read_b128 v[198:201], v169 offset:20480
	ds_read_b128 v[208:211], v169 offset:21504
	ds_read_b128 v[212:215], v169 offset:22528
	ds_read_b128 v[216:219], v169 offset:23552
	global_load_lds_dwordx4 v[158:159], off
	s_add_i32 m0, s78, 0x2000
	s_add_u32 vcc_lo, s22, 0x40000
	v_lshl_add_u64 v[162:163], s[22:23], 0, v[128:129]
	s_addc_u32 vcc_hi, s23, 0
	s_add_i32 s78, s79, s28
	global_load_lds_dwordx4 v[162:163], off
	v_lshl_add_u64 v[202:203], vcc, 0, v[160:161]
	s_mov_b32 m0, s78
	v_lshl_add_u64 v[206:207], s[24:25], 0, v[130:131]
	global_load_lds_dwordx4 v[202:203], off
	v_lshl_add_u64 v[202:203], vcc, 0, v[128:129]
	s_add_i32 m0, s78, 0x2000
	s_nop 0
	global_load_lds_dwordx4 v[202:203], off
	v_lshl_add_u64 v[202:203], s[24:25], 0, v[132:133]
	s_mov_b32 m0, s29
	s_nop 0
	global_load_lds_dwordx4 v[202:203], off
	s_mov_b32 m0, s30
	s_nop 0
	global_load_lds_dwordx4 v[206:207], off
	s_cmp_eq_u32 s99, 1
	s_cbranch_scc1 .Lskipw_p4a_1
	s_waitcnt vmcnt(8)
.Lskipw_p4a_1:
	s_mov_b32 s99, 0
	s_waitcnt lgkmcnt(0)
	s_barrier
	s_setprio 1
	s_waitcnt lgkmcnt(0)
	v_mfma_f32_16x16x32_bf16 v[60:63], v[138:141], v[182:185], v[60:63]
	v_mfma_f32_16x16x32_bf16 v[56:59], v[146:149], v[182:185], v[56:59]
	v_mfma_f32_16x16x32_bf16 v[44:47], v[138:141], v[190:193], v[44:47]
	v_mfma_f32_16x16x32_bf16 v[40:43], v[146:149], v[190:193], v[40:43]
	v_mfma_f32_16x16x32_bf16 v[28:31], v[138:141], v[198:201], v[28:31]
	v_mfma_f32_16x16x32_bf16 v[24:27], v[146:149], v[198:201], v[24:27]
	v_mfma_f32_16x16x32_bf16 v[12:15], v[138:141], v[212:215], v[12:15]
	v_mfma_f32_16x16x32_bf16 v[8:11], v[146:149], v[212:215], v[8:11]
	v_mfma_f32_16x16x32_bf16 v[60:63], v[142:145], v[186:189], v[60:63]
	v_mfma_f32_16x16x32_bf16 v[56:59], v[150:153], v[186:189], v[56:59]
	v_mfma_f32_16x16x32_bf16 v[44:47], v[142:145], v[194:197], v[44:47]
	v_mfma_f32_16x16x32_bf16 v[40:43], v[150:153], v[194:197], v[40:43]
	v_mfma_f32_16x16x32_bf16 v[28:31], v[142:145], v[208:211], v[28:31]
	v_mfma_f32_16x16x32_bf16 v[24:27], v[150:153], v[208:211], v[24:27]
	v_mfma_f32_16x16x32_bf16 v[12:15], v[142:145], v[216:219], v[12:15]
	v_mfma_f32_16x16x32_bf16 v[8:11], v[150:153], v[216:219], v[8:11]
	s_setprio 0
	s_setprio 1
	v_mfma_f32_16x16x32_bf16 v[52:55], v[154:157], v[182:185], v[52:55]
	v_mfma_f32_16x16x32_bf16 v[48:51], v[174:177], v[182:185], v[48:51]
	v_mfma_f32_16x16x32_bf16 v[36:39], v[154:157], v[190:193], v[36:39]
	v_mfma_f32_16x16x32_bf16 v[32:35], v[174:177], v[190:193], v[32:35]
	v_mfma_f32_16x16x32_bf16 v[20:23], v[154:157], v[198:201], v[20:23]
	v_mfma_f32_16x16x32_bf16 v[16:19], v[174:177], v[198:201], v[16:19]
	v_mfma_f32_16x16x32_bf16 v[4:7], v[154:157], v[212:215], v[4:7]
	v_mfma_f32_16x16x32_bf16 v[0:3], v[174:177], v[212:215], v[0:3]
	v_mfma_f32_16x16x32_bf16 v[52:55], v[170:173], v[186:189], v[52:55]
	v_mfma_f32_16x16x32_bf16 v[48:51], v[178:181], v[186:189], v[48:51]
	v_mfma_f32_16x16x32_bf16 v[36:39], v[170:173], v[194:197], v[36:39]
	v_mfma_f32_16x16x32_bf16 v[32:35], v[178:181], v[194:197], v[32:35]
	v_mfma_f32_16x16x32_bf16 v[20:23], v[170:173], v[208:211], v[20:23]
	v_mfma_f32_16x16x32_bf16 v[16:19], v[178:181], v[208:211], v[16:19]
	v_mfma_f32_16x16x32_bf16 v[4:7], v[170:173], v[216:219], v[4:7]
	v_mfma_f32_16x16x32_bf16 v[0:3], v[178:181], v[216:219], v[0:3]
	s_setprio 0
	s_barrier
	s_add_i32 s78, 0, 0x18000
	s_add_i32 s79, 0, 0x1c000
	v_add_u32_e32 v150, s78, v167
	v_add_u32_e32 v178, s79, v167
	ds_read_b128 v[138:141], v150
	ds_read_b128 v[142:145], v150 offset:1024
	ds_read_b128 v[146:149], v150 offset:2048
	ds_read_b128 v[150:153], v150 offset:3072
	ds_read_b128 v[154:157], v178
	ds_read_b128 v[170:173], v178 offset:1024
	ds_read_b128 v[174:177], v178 offset:2048
	ds_read_b128 v[178:181], v178 offset:3072
	s_add_u32 s24, s24, 0x40000
	s_addc_u32 s25, s25, 0
	s_mov_b32 m0, s31
	v_lshl_add_u64 v[220:221], s[24:25], 0, v[132:133]
	ds_read_b128 v[182:185], v169 offset:32768
	ds_read_b128 v[186:189], v169 offset:33792
	ds_read_b128 v[190:193], v169 offset:34816
	ds_read_b128 v[194:197], v169 offset:35840
	ds_read_b128 v[198:201], v169 offset:36864
	ds_read_b128 v[208:211], v169 offset:37888
	ds_read_b128 v[212:215], v169 offset:38912
	ds_read_b128 v[216:219], v169 offset:39936
	global_load_lds_dwordx4 v[220:221], off
	v_lshl_add_u64 v[220:221], s[24:25], 0, v[130:131]
	s_mov_b32 m0, s34
	s_nop 0
	global_load_lds_dwordx4 v[220:221], off
	s_waitcnt vmcnt(8)
	s_waitcnt lgkmcnt(0)
	s_barrier
	s_setprio 1
	s_waitcnt lgkmcnt(0)
	v_mfma_f32_16x16x32_bf16 v[124:127], v[138:141], v[182:185], v[124:127]
	v_mfma_f32_16x16x32_bf16 v[120:123], v[146:149], v[182:185], v[120:123]
	v_mfma_f32_16x16x32_bf16 v[108:111], v[138:141], v[190:193], v[108:111]
	v_mfma_f32_16x16x32_bf16 v[104:107], v[146:149], v[190:193], v[104:107]
	v_mfma_f32_16x16x32_bf16 v[92:95], v[138:141], v[198:201], v[92:95]
	v_mfma_f32_16x16x32_bf16 v[88:91], v[146:149], v[198:201], v[88:91]
	v_mfma_f32_16x16x32_bf16 v[76:79], v[138:141], v[212:215], v[76:79]
	v_mfma_f32_16x16x32_bf16 v[72:75], v[146:149], v[212:215], v[72:75]
	v_mfma_f32_16x16x32_bf16 v[124:127], v[142:145], v[186:189], v[124:127]
	v_mfma_f32_16x16x32_bf16 v[120:123], v[150:153], v[186:189], v[120:123]
	v_mfma_f32_16x16x32_bf16 v[108:111], v[142:145], v[194:197], v[108:111]
	v_mfma_f32_16x16x32_bf16 v[104:107], v[150:153], v[194:197], v[104:107]
	v_mfma_f32_16x16x32_bf16 v[92:95], v[142:145], v[208:211], v[92:95]
	v_mfma_f32_16x16x32_bf16 v[88:91], v[150:153], v[208:211], v[88:91]
	v_mfma_f32_16x16x32_bf16 v[76:79], v[142:145], v[216:219], v[76:79]
	v_mfma_f32_16x16x32_bf16 v[72:75], v[150:153], v[216:219], v[72:75]
	s_setprio 0
	s_setprio 1
	v_mfma_f32_16x16x32_bf16 v[116:119], v[154:157], v[182:185], v[116:119]
	v_mfma_f32_16x16x32_bf16 v[112:115], v[174:177], v[182:185], v[112:115]
	v_mfma_f32_16x16x32_bf16 v[100:103], v[154:157], v[190:193], v[100:103]
	v_mfma_f32_16x16x32_bf16 v[96:99], v[174:177], v[190:193], v[96:99]
	v_mfma_f32_16x16x32_bf16 v[84:87], v[154:157], v[198:201], v[84:87]
	v_mfma_f32_16x16x32_bf16 v[80:83], v[174:177], v[198:201], v[80:83]
	v_mfma_f32_16x16x32_bf16 v[68:71], v[154:157], v[212:215], v[68:71]
	v_mfma_f32_16x16x32_bf16 v[64:67], v[174:177], v[212:215], v[64:67]
	v_mfma_f32_16x16x32_bf16 v[116:119], v[170:173], v[186:189], v[116:119]
	v_mfma_f32_16x16x32_bf16 v[112:115], v[178:181], v[186:189], v[112:115]
	v_mfma_f32_16x16x32_bf16 v[100:103], v[170:173], v[194:197], v[100:103]
	v_mfma_f32_16x16x32_bf16 v[96:99], v[178:181], v[194:197], v[96:99]
	v_mfma_f32_16x16x32_bf16 v[84:87], v[170:173], v[208:211], v[84:87]
	v_mfma_f32_16x16x32_bf16 v[80:83], v[178:181], v[208:211], v[80:83]
	v_mfma_f32_16x16x32_bf16 v[68:71], v[170:173], v[216:219], v[68:71]
	v_mfma_f32_16x16x32_bf16 v[64:67], v[178:181], v[216:219], v[64:67]
	s_setprio 0
	s_barrier
	s_add_i32 s24, s78, s28
	v_lshl_add_u64 v[158:159], v[158:159], 0, s[38:39]
	s_mov_b32 m0, s24
	ds_read_b128 v[182:185], v169 offset:49152
	ds_read_b128 v[186:189], v169 offset:50176
	ds_read_b128 v[190:193], v169 offset:51200
	ds_read_b128 v[194:197], v169 offset:52224
	ds_read_b128 v[198:201], v169 offset:53248
	ds_read_b128 v[208:211], v169 offset:54272
	ds_read_b128 v[212:215], v169 offset:55296
	ds_read_b128 v[216:219], v169 offset:56320
	global_load_lds_dwordx4 v[158:159], off
	s_add_i32 m0, s24, 0x2000
	s_add_u32 s22, s22, 0x40080
	v_lshl_add_u64 v[158:159], v[162:163], 0, s[38:39]
	s_addc_u32 s23, s23, 0
	s_add_i32 s24, s79, s28
	global_load_lds_dwordx4 v[158:159], off
	v_lshl_add_u64 v[158:159], s[22:23], 0, v[160:161]
	s_mov_b32 m0, s24
	s_nop 0
	global_load_lds_dwordx4 v[158:159], off
	v_lshl_add_u64 v[158:159], s[22:23], 0, v[128:129]
	s_add_i32 m0, s24, 0x2000
	s_nop 0
	global_load_lds_dwordx4 v[158:159], off
	v_lshl_add_u64 v[158:159], v[202:203], 0, s[38:39]
	s_mov_b32 m0, s85
	s_nop 0
	global_load_lds_dwordx4 v[158:159], off
	v_lshl_add_u64 v[158:159], v[206:207], 0, s[38:39]
	s_mov_b32 m0, s86
	s_nop 0
	global_load_lds_dwordx4 v[158:159], off
	s_waitcnt vmcnt(8)
	s_waitcnt lgkmcnt(0)
	s_barrier
	s_setprio 1
	s_waitcnt lgkmcnt(0)
	v_mfma_f32_16x16x32_bf16 v[60:63], v[138:141], v[182:185], v[60:63]
	v_mfma_f32_16x16x32_bf16 v[56:59], v[146:149], v[182:185], v[56:59]
	v_mfma_f32_16x16x32_bf16 v[44:47], v[138:141], v[190:193], v[44:47]
	v_mfma_f32_16x16x32_bf16 v[40:43], v[146:149], v[190:193], v[40:43]
	v_mfma_f32_16x16x32_bf16 v[28:31], v[138:141], v[198:201], v[28:31]
	v_mfma_f32_16x16x32_bf16 v[24:27], v[146:149], v[198:201], v[24:27]
	v_mfma_f32_16x16x32_bf16 v[12:15], v[138:141], v[212:215], v[12:15]
	v_mfma_f32_16x16x32_bf16 v[8:11], v[146:149], v[212:215], v[8:11]
	v_mfma_f32_16x16x32_bf16 v[60:63], v[142:145], v[186:189], v[60:63]
	v_mfma_f32_16x16x32_bf16 v[56:59], v[150:153], v[186:189], v[56:59]
	v_mfma_f32_16x16x32_bf16 v[44:47], v[142:145], v[194:197], v[44:47]
	v_mfma_f32_16x16x32_bf16 v[40:43], v[150:153], v[194:197], v[40:43]
	v_mfma_f32_16x16x32_bf16 v[28:31], v[142:145], v[208:211], v[28:31]
	v_mfma_f32_16x16x32_bf16 v[24:27], v[150:153], v[208:211], v[24:27]
	v_mfma_f32_16x16x32_bf16 v[12:15], v[142:145], v[216:219], v[12:15]
	v_mfma_f32_16x16x32_bf16 v[8:11], v[150:153], v[216:219], v[8:11]
	s_setprio 0
	s_setprio 1
	v_mfma_f32_16x16x32_bf16 v[52:55], v[154:157], v[182:185], v[52:55]
	v_mfma_f32_16x16x32_bf16 v[48:51], v[174:177], v[182:185], v[48:51]
	v_mfma_f32_16x16x32_bf16 v[36:39], v[154:157], v[190:193], v[36:39]
	v_mfma_f32_16x16x32_bf16 v[32:35], v[174:177], v[190:193], v[32:35]
	v_mfma_f32_16x16x32_bf16 v[20:23], v[154:157], v[198:201], v[20:23]
	v_mfma_f32_16x16x32_bf16 v[16:19], v[174:177], v[198:201], v[16:19]
	v_mfma_f32_16x16x32_bf16 v[4:7], v[154:157], v[212:215], v[4:7]
	v_mfma_f32_16x16x32_bf16 v[0:3], v[174:177], v[212:215], v[0:3]
	v_mfma_f32_16x16x32_bf16 v[52:55], v[170:173], v[186:189], v[52:55]
	v_mfma_f32_16x16x32_bf16 v[48:51], v[178:181], v[186:189], v[48:51]
	v_mfma_f32_16x16x32_bf16 v[36:39], v[170:173], v[194:197], v[36:39]
	v_mfma_f32_16x16x32_bf16 v[32:35], v[178:181], v[194:197], v[32:35]
	v_mfma_f32_16x16x32_bf16 v[20:23], v[170:173], v[208:211], v[20:23]
	v_mfma_f32_16x16x32_bf16 v[16:19], v[178:181], v[208:211], v[16:19]
	v_mfma_f32_16x16x32_bf16 v[4:7], v[170:173], v[216:219], v[4:7]
	v_mfma_f32_16x16x32_bf16 v[0:3], v[178:181], v[216:219], v[0:3]
	s_setprio 0
	s_barrier
	s_add_i32 s90, s90, 2
	s_add_u32 s20, s20, 0x100
	s_addc_u32 s21, s21, 0
	s_add_u32 s95, s95, 0x100
	s_addc_u32 s96, s96, 0
	s_cmp_gt_u32 s90, 13
	s_cbranch_scc0 .LBB0_479
	s_and_b64 vcc, exec, s[10:11]
	s_cbranch_vccz .LBB0_482
	s_barrier

.LBB0_507:
	v_lshrrev_b32_e32 v16, 1, v10
	v_and_b32_e32 v16, 24, v16
	v_and_b32_e32 v11, 15, v10
	v_lshlrev_b32_e32 v17, 1, v16
	v_lshlrev_b32_e32 v10, 2, v10
	s_lshl_b32 s3, s3, 5
	v_lshl_or_b32 v166, s4, 6, v11
	v_lshl_or_b32 v11, v11, 6, v17
	s_lshl_b32 s4, s4, 13
	v_and_b32_e32 v10, 32, v10
	s_and_b32 s3, s3, 0x60
	v_bitop3_b32 v17, v11, s4, v10 bitop3:0xde
	s_lshl_b32 s4, s3, 7
	v_readlane_b32 s18, v254, 21
	s_add_u32 s31, s65, 0x5400
	v_mov_b32_e32 v133, v161
	v_readlane_b32 s19, v254, 22
	s_addc_u32 s34, s94, 0
	s_add_i32 m0, s27, 0x18000
	v_lshl_add_u64 v[0:1], v[0:1], 0, s[38:39]
	v_lshl_add_u64 v[12:13], s[18:19], 0, v[132:133]
	v_mov_b32_e32 v131, v161
	global_load_lds_dwordx4 v[0:1], off
	v_lshl_add_u64 v[0:1], v[2:3], 0, s[38:39]
	s_add_i32 m0, s27, 0x1a000
	s_add_i32 s35, s27, 0x8000
	s_add_i32 s65, s27, 0xa000
	v_lshl_add_u64 v[14:15], s[18:19], 0, v[130:131]
	v_bitop3_b32 v167, v11, s4, v10 bitop3:0xde
	global_load_lds_dwordx4 v[0:1], off
	v_lshl_add_u64 v[0:1], v[12:13], 0, s[38:39]
	s_mov_b32 m0, s35
	s_add_u32 s4, s20, 0x40080
	global_load_lds_dwordx4 v[0:1], off
	v_lshl_add_u64 v[0:1], v[14:15], 0, s[38:39]
	s_mov_b32 m0, s65
	s_addc_u32 s5, s21, 0
	global_load_lds_dwordx4 v[0:1], off
	s_add_i32 m0, s27, 0x1c000
	v_lshl_add_u64 v[0:1], s[4:5], 0, v[160:161]
	global_load_lds_dwordx4 v[0:1], off
	v_lshl_add_u64 v[0:1], s[4:5], 0, v[128:129]
	s_add_i32 m0, s27, 0x1e000
	s_cmpk_lt_u32 s2, 0x100
	global_load_lds_dwordx4 v[0:1], off
	s_waitcnt vmcnt(8)
	s_barrier
	v_lshlrev_b32_e32 v0, 14, v8
	v_and_b32_e32 v0, 0xffff8000, v0
	v_lshl_add_u32 v0, v7, 11, v0
	v_and_b32_e32 v1, 1, v8
	v_lshl_or_b32 v0, v1, 6, v0
	v_lshl_add_u32 v134, v9, 1, v0
	v_lshlrev_b32_e32 v0, 14, v4
	v_and_b32_e32 v0, 0xffff8000, v0
	s_waitcnt vmcnt(6)
	v_lshl_add_u32 v0, v5, 11, v0
	v_and_b32_e32 v1, 1, v4
	v_lshl_or_b32 v0, v1, 6, v0
	v_readlane_b32 s4, v254, 58
	s_cselect_b64 s[8:9], -1, 0
	v_or_b32_e32 v168, s3, v16
	v_mov_b32_e32 v135, v161
	v_lshl_add_u32 v136, v6, 1, v0
	v_mov_b32_e32 v137, v161
	s_mov_b32 s84, 0
	v_add_u32_e32 v169, 0, v17
	v_readlane_b32 s3, v254, 18
	s_mov_b32 s2, s4
	s_barrier
	v_readlane_b32 s5, v254, 59
	s_mov_b32 s99, 0
	s_branch .LBB0_510

.LBB0_509:
	s_mov_b32 s99, 1
	s_andn2_b64 vcc, exec, s[18:19]
	s_mov_b32 s3, s10
	s_mov_b32 s2, s12
	s_mov_b64 s[20:21], s[16:17]
	s_mov_b64 s[18:19], s[14:15]
	s_cbranch_vccz .LBB0_523

.LBB0_517:
	s_add_u32 s20, s18, 0xfffc0080
	s_addc_u32 s21, s19, -1
	s_add_i32 s78, 0, 0x10000
	s_cmp_eq_u32 s89, 12
	s_cselect_b32 s23, s13, s21
	s_cselect_b32 s22, s56, s20
	s_cselect_b32 s21, s11, s88
	s_cselect_b32 s20, s85, s86
	s_add_i32 s79, 0, 0x14000
	v_add_u32_e32 v150, s78, v167
	v_add_u32_e32 v158, s79, v167
	ds_read_b128 v[138:141], v150
	ds_read_b128 v[142:145], v150 offset:1024
	ds_read_b128 v[146:149], v150 offset:2048
	ds_read_b128 v[150:153], v150 offset:3072
	ds_read_b128 v[154:157], v158
	ds_read_b128 v[170:173], v158 offset:1024
	ds_read_b128 v[174:177], v158 offset:2048
	ds_read_b128 v[178:181], v158 offset:3072
	v_lshl_add_u64 v[158:159], s[18:19], 0, v[134:135]
	s_add_i32 m0, s27, 0xc000
	ds_read_b128 v[182:185], v169
	ds_read_b128 v[186:189], v169 offset:1024
	ds_read_b128 v[190:193], v169 offset:2048
	ds_read_b128 v[194:197], v169 offset:3072
	ds_read_b128 v[198:201], v169 offset:4096
	ds_read_b128 v[208:211], v169 offset:5120
	ds_read_b128 v[212:215], v169 offset:6144
	ds_read_b128 v[216:219], v169 offset:7168
	global_load_lds_dwordx4 v[158:159], off
	v_lshl_add_u64 v[158:159], s[18:19], 0, v[136:137]
	s_add_i32 m0, s27, 0xe000
	s_nop 0
	global_load_lds_dwordx4 v[158:159], off
	s_cmp_eq_u32 s99, 1
	s_cbranch_scc1 .Lskipw_p4c_0
	s_waitcnt vmcnt(8)
.Lskipw_p4c_0:
	s_waitcnt lgkmcnt(0)
	s_barrier
	s_setprio 1
	s_waitcnt lgkmcnt(0)
	v_mfma_f32_16x16x32_bf16 v[124:127], v[138:141], v[182:185], v[124:127]
	v_mfma_f32_16x16x32_bf16 v[120:123], v[146:149], v[182:185], v[120:123]
	v_mfma_f32_16x16x32_bf16 v[108:111], v[138:141], v[190:193], v[108:111]
	v_mfma_f32_16x16x32_bf16 v[104:107], v[146:149], v[190:193], v[104:107]
	v_mfma_f32_16x16x32_bf16 v[92:95], v[138:141], v[198:201], v[92:95]
	v_mfma_f32_16x16x32_bf16 v[88:91], v[146:149], v[198:201], v[88:91]
	v_mfma_f32_16x16x32_bf16 v[76:79], v[138:141], v[212:215], v[76:79]
	v_mfma_f32_16x16x32_bf16 v[72:75], v[146:149], v[212:215], v[72:75]
	v_mfma_f32_16x16x32_bf16 v[124:127], v[142:145], v[186:189], v[124:127]
	v_mfma_f32_16x16x32_bf16 v[120:123], v[150:153], v[186:189], v[120:123]
	v_mfma_f32_16x16x32_bf16 v[108:111], v[142:145], v[194:197], v[108:111]
	v_mfma_f32_16x16x32_bf16 v[104:107], v[150:153], v[194:197], v[104:107]
	v_mfma_f32_16x16x32_bf16 v[92:95], v[142:145], v[208:211], v[92:95]
	v_mfma_f32_16x16x32_bf16 v[88:91], v[150:153], v[208:211], v[88:91]
	v_mfma_f32_16x16x32_bf16 v[76:79], v[142:145], v[216:219], v[76:79]
	v_mfma_f32_16x16x32_bf16 v[72:75], v[150:153], v[216:219], v[72:75]
	s_setprio 0
	s_setprio 1
	v_mfma_f32_16x16x32_bf16 v[116:119], v[154:157], v[182:185], v[116:119]
	v_mfma_f32_16x16x32_bf16 v[112:115], v[174:177], v[182:185], v[112:115]
	v_mfma_f32_16x16x32_bf16 v[100:103], v[154:157], v[190:193], v[100:103]
	v_mfma_f32_16x16x32_bf16 v[96:99], v[174:177], v[190:193], v[96:99]
	v_mfma_f32_16x16x32_bf16 v[84:87], v[154:157], v[198:201], v[84:87]
	v_mfma_f32_16x16x32_bf16 v[80:83], v[174:177], v[198:201], v[80:83]
	v_mfma_f32_16x16x32_bf16 v[68:71], v[154:157], v[212:215], v[68:71]
	v_mfma_f32_16x16x32_bf16 v[64:67], v[174:177], v[212:215], v[64:67]
	v_mfma_f32_16x16x32_bf16 v[116:119], v[170:173], v[186:189], v[116:119]
	v_mfma_f32_16x16x32_bf16 v[112:115], v[178:181], v[186:189], v[112:115]
	v_mfma_f32_16x16x32_bf16 v[100:103], v[170:173], v[194:197], v[100:103]
	v_mfma_f32_16x16x32_bf16 v[96:99], v[178:181], v[194:197], v[96:99]
	v_mfma_f32_16x16x32_bf16 v[84:87], v[170:173], v[208:211], v[84:87]
	v_mfma_f32_16x16x32_bf16 v[80:83], v[178:181], v[208:211], v[80:83]
	v_mfma_f32_16x16x32_bf16 v[68:71], v[170:173], v[216:219], v[68:71]
	v_mfma_f32_16x16x32_bf16 v[64:67], v[178:181], v[216:219], v[64:67]
	s_setprio 0
	s_barrier
	s_add_i32 s78, s78, s26
	v_lshl_add_u64 v[158:159], s[20:21], 0, v[160:161]
	s_mov_b32 m0, s78
	ds_read_b128 v[182:185], v169 offset:16384
	ds_read_b128 v[186:189], v169 offset:17408
	ds_read_b128 v[190:193], v169 offset:18432
	ds_read_b128 v[194:197], v169 offset:19456
	ds_read_b128 v[198:201], v169 offset:20480
	ds_read_b128 v[208:211], v169 offset:21504
	ds_read_b128 v[212:215], v169 offset:22528
	ds_read_b128 v[216:219], v169 offset:23552
	global_load_lds_dwordx4 v[158:159], off
	s_add_i32 m0, s78, 0x2000
	s_add_u32 s90, s20, 0x40000
	v_lshl_add_u64 v[162:163], s[20:21], 0, v[128:129]
	s_addc_u32 s91, s21, 0
	s_add_i32 s78, s79, s26
	global_load_lds_dwordx4 v[162:163], off
	v_lshl_add_u64 v[202:203], s[90:91], 0, v[160:161]
	s_mov_b32 m0, s78
	v_lshl_add_u64 v[206:207], s[22:23], 0, v[130:131]
	global_load_lds_dwordx4 v[202:203], off
	v_lshl_add_u64 v[202:203], s[90:91], 0, v[128:129]
	s_add_i32 m0, s78, 0x2000
	s_nop 0
	global_load_lds_dwordx4 v[202:203], off
	v_lshl_add_u64 v[202:203], s[22:23], 0, v[132:133]
	s_mov_b32 m0, s27
	s_nop 0
	global_load_lds_dwordx4 v[202:203], off
	s_mov_b32 m0, s28
	s_nop 0
	global_load_lds_dwordx4 v[206:207], off
	s_cmp_eq_u32 s99, 1
	s_cbranch_scc1 .Lskipw_p4c_1
	s_waitcnt vmcnt(8)
.Lskipw_p4c_1:
	s_mov_b32 s99, 0
	s_waitcnt lgkmcnt(0)
	s_barrier
	s_setprio 1
	s_waitcnt lgkmcnt(0)
	v_mfma_f32_16x16x32_bf16 v[60:63], v[138:141], v[182:185], v[60:63]
	v_mfma_f32_16x16x32_bf16 v[56:59], v[146:149], v[182:185], v[56:59]
	v_mfma_f32_16x16x32_bf16 v[44:47], v[138:141], v[190:193], v[44:47]
	v_mfma_f32_16x16x32_bf16 v[40:43], v[146:149], v[190:193], v[40:43]
	v_mfma_f32_16x16x32_bf16 v[28:31], v[138:141], v[198:201], v[28:31]
	v_mfma_f32_16x16x32_bf16 v[24:27], v[146:149], v[198:201], v[24:27]
	v_mfma_f32_16x16x32_bf16 v[12:15], v[138:141], v[212:215], v[12:15]
	v_mfma_f32_16x16x32_bf16 v[8:11], v[146:149], v[212:215], v[8:11]
	v_mfma_f32_16x16x32_bf16 v[60:63], v[142:145], v[186:189], v[60:63]
	v_mfma_f32_16x16x32_bf16 v[56:59], v[150:153], v[186:189], v[56:59]
	v_mfma_f32_16x16x32_bf16 v[44:47], v[142:145], v[194:197], v[44:47]
	v_mfma_f32_16x16x32_bf16 v[40:43], v[150:153], v[194:197], v[40:43]
	v_mfma_f32_16x16x32_bf16 v[28:31], v[142:145], v[208:211], v[28:31]
	v_mfma_f32_16x16x32_bf16 v[24:27], v[150:153], v[208:211], v[24:27]
	v_mfma_f32_16x16x32_bf16 v[12:15], v[142:145], v[216:219], v[12:15]
	v_mfma_f32_16x16x32_bf16 v[8:11], v[150:153], v[216:219], v[8:11]
	s_setprio 0
	s_setprio 1
	v_mfma_f32_16x16x32_bf16 v[52:55], v[154:157], v[182:185], v[52:55]
	v_mfma_f32_16x16x32_bf16 v[48:51], v[174:177], v[182:185], v[48:51]
	v_mfma_f32_16x16x32_bf16 v[36:39], v[154:157], v[190:193], v[36:39]
	v_mfma_f32_16x16x32_bf16 v[32:35], v[174:177], v[190:193], v[32:35]
	v_mfma_f32_16x16x32_bf16 v[20:23], v[154:157], v[198:201], v[20:23]
	v_mfma_f32_16x16x32_bf16 v[16:19], v[174:177], v[198:201], v[16:19]
	v_mfma_f32_16x16x32_bf16 v[4:7], v[154:157], v[212:215], v[4:7]
	v_mfma_f32_16x16x32_bf16 v[0:3], v[174:177], v[212:215], v[0:3]
	v_mfma_f32_16x16x32_bf16 v[52:55], v[170:173], v[186:189], v[52:55]
	v_mfma_f32_16x16x32_bf16 v[48:51], v[178:181], v[186:189], v[48:51]
	v_mfma_f32_16x16x32_bf16 v[36:39], v[170:173], v[194:197], v[36:39]
	v_mfma_f32_16x16x32_bf16 v[32:35], v[178:181], v[194:197], v[32:35]
	v_mfma_f32_16x16x32_bf16 v[20:23], v[170:173], v[208:211], v[20:23]
	v_mfma_f32_16x16x32_bf16 v[16:19], v[178:181], v[208:211], v[16:19]
	v_mfma_f32_16x16x32_bf16 v[4:7], v[170:173], v[216:219], v[4:7]
	v_mfma_f32_16x16x32_bf16 v[0:3], v[178:181], v[216:219], v[0:3]
	s_setprio 0
	s_barrier
	s_add_i32 s78, 0, 0x18000
	s_add_i32 s79, 0, 0x1c000
	v_add_u32_e32 v150, s78, v167
	v_add_u32_e32 v178, s79, v167
	ds_read_b128 v[138:141], v150
	ds_read_b128 v[142:145], v150 offset:1024
	ds_read_b128 v[146:149], v150 offset:2048
	ds_read_b128 v[150:153], v150 offset:3072
	ds_read_b128 v[154:157], v178
	ds_read_b128 v[170:173], v178 offset:1024
	ds_read_b128 v[174:177], v178 offset:2048
	ds_read_b128 v[178:181], v178 offset:3072
	s_add_u32 s22, s22, 0x40000
	s_addc_u32 s23, s23, 0
	s_mov_b32 m0, s29
	v_lshl_add_u64 v[220:221], s[22:23], 0, v[132:133]
	ds_read_b128 v[182:185], v169 offset:32768
	ds_read_b128 v[186:189], v169 offset:33792
	ds_read_b128 v[190:193], v169 offset:34816
	ds_read_b128 v[194:197], v169 offset:35840
	ds_read_b128 v[198:201], v169 offset:36864
	ds_read_b128 v[208:211], v169 offset:37888
	ds_read_b128 v[212:215], v169 offset:38912
	ds_read_b128 v[216:219], v169 offset:39936
	global_load_lds_dwordx4 v[220:221], off
	v_lshl_add_u64 v[220:221], s[22:23], 0, v[130:131]
	s_mov_b32 m0, s30
	s_nop 0
	global_load_lds_dwordx4 v[220:221], off
	s_waitcnt vmcnt(8)
	s_waitcnt lgkmcnt(0)
	s_barrier
	s_setprio 1
	s_waitcnt lgkmcnt(0)
	v_mfma_f32_16x16x32_bf16 v[124:127], v[138:141], v[182:185], v[124:127]
	v_mfma_f32_16x16x32_bf16 v[120:123], v[146:149], v[182:185], v[120:123]
	v_mfma_f32_16x16x32_bf16 v[108:111], v[138:141], v[190:193], v[108:111]
	v_mfma_f32_16x16x32_bf16 v[104:107], v[146:149], v[190:193], v[104:107]
	v_mfma_f32_16x16x32_bf16 v[92:95], v[138:141], v[198:201], v[92:95]
	v_mfma_f32_16x16x32_bf16 v[88:91], v[146:149], v[198:201], v[88:91]
	v_mfma_f32_16x16x32_bf16 v[76:79], v[138:141], v[212:215], v[76:79]
	v_mfma_f32_16x16x32_bf16 v[72:75], v[146:149], v[212:215], v[72:75]
	v_mfma_f32_16x16x32_bf16 v[124:127], v[142:145], v[186:189], v[124:127]
	v_mfma_f32_16x16x32_bf16 v[120:123], v[150:153], v[186:189], v[120:123]
	v_mfma_f32_16x16x32_bf16 v[108:111], v[142:145], v[194:197], v[108:111]
	v_mfma_f32_16x16x32_bf16 v[104:107], v[150:153], v[194:197], v[104:107]
	v_mfma_f32_16x16x32_bf16 v[92:95], v[142:145], v[208:211], v[92:95]
	v_mfma_f32_16x16x32_bf16 v[88:91], v[150:153], v[208:211], v[88:91]
	v_mfma_f32_16x16x32_bf16 v[76:79], v[142:145], v[216:219], v[76:79]
	v_mfma_f32_16x16x32_bf16 v[72:75], v[150:153], v[216:219], v[72:75]
	s_setprio 0
	s_setprio 1
	v_mfma_f32_16x16x32_bf16 v[116:119], v[154:157], v[182:185], v[116:119]
	v_mfma_f32_16x16x32_bf16 v[112:115], v[174:177], v[182:185], v[112:115]
	v_mfma_f32_16x16x32_bf16 v[100:103], v[154:157], v[190:193], v[100:103]
	v_mfma_f32_16x16x32_bf16 v[96:99], v[174:177], v[190:193], v[96:99]
	v_mfma_f32_16x16x32_bf16 v[84:87], v[154:157], v[198:201], v[84:87]
	v_mfma_f32_16x16x32_bf16 v[80:83], v[174:177], v[198:201], v[80:83]
	v_mfma_f32_16x16x32_bf16 v[68:71], v[154:157], v[212:215], v[68:71]
	v_mfma_f32_16x16x32_bf16 v[64:67], v[174:177], v[212:215], v[64:67]
	v_mfma_f32_16x16x32_bf16 v[116:119], v[170:173], v[186:189], v[116:119]
	v_mfma_f32_16x16x32_bf16 v[112:115], v[178:181], v[186:189], v[112:115]
	v_mfma_f32_16x16x32_bf16 v[100:103], v[170:173], v[194:197], v[100:103]
	v_mfma_f32_16x16x32_bf16 v[96:99], v[178:181], v[194:197], v[96:99]
	v_mfma_f32_16x16x32_bf16 v[84:87], v[170:173], v[208:211], v[84:87]
	v_mfma_f32_16x16x32_bf16 v[80:83], v[178:181], v[208:211], v[80:83]
	v_mfma_f32_16x16x32_bf16 v[68:71], v[170:173], v[216:219], v[68:71]
	v_mfma_f32_16x16x32_bf16 v[64:67], v[178:181], v[216:219], v[64:67]
	s_setprio 0
	s_barrier
	s_add_i32 s22, s78, s26
	v_lshl_add_u64 v[158:159], v[158:159], 0, s[38:39]
	s_mov_b32 m0, s22
	ds_read_b128 v[182:185], v169 offset:49152
	ds_read_b128 v[186:189], v169 offset:50176
	ds_read_b128 v[190:193], v169 offset:51200
	ds_read_b128 v[194:197], v169 offset:52224
	ds_read_b128 v[198:201], v169 offset:53248
	ds_read_b128 v[208:211], v169 offset:54272
	ds_read_b128 v[212:215], v169 offset:55296
	ds_read_b128 v[216:219], v169 offset:56320
	global_load_lds_dwordx4 v[158:159], off
	s_add_i32 m0, s22, 0x2000
	s_add_u32 s20, s20, 0x40080
	v_lshl_add_u64 v[158:159], v[162:163], 0, s[38:39]
	s_addc_u32 s21, s21, 0
	s_add_i32 s22, s79, s26
	global_load_lds_dwordx4 v[158:159], off
	v_lshl_add_u64 v[158:159], s[20:21], 0, v[160:161]
	s_mov_b32 m0, s22
	s_nop 0
	global_load_lds_dwordx4 v[158:159], off
	v_lshl_add_u64 v[158:159], s[20:21], 0, v[128:129]
	s_add_i32 m0, s22, 0x2000
	s_nop 0
	global_load_lds_dwordx4 v[158:159], off
	v_lshl_add_u64 v[158:159], v[202:203], 0, s[38:39]
	s_mov_b32 m0, s35
	s_nop 0
	global_load_lds_dwordx4 v[158:159], off
	v_lshl_add_u64 v[158:159], v[206:207], 0, s[38:39]
	s_mov_b32 m0, s65
	s_nop 0
	global_load_lds_dwordx4 v[158:159], off
	s_waitcnt vmcnt(8)
	s_waitcnt lgkmcnt(0)
	s_barrier
	s_setprio 1
	s_waitcnt lgkmcnt(0)
	v_mfma_f32_16x16x32_bf16 v[60:63], v[138:141], v[182:185], v[60:63]
	v_mfma_f32_16x16x32_bf16 v[56:59], v[146:149], v[182:185], v[56:59]
	v_mfma_f32_16x16x32_bf16 v[44:47], v[138:141], v[190:193], v[44:47]
	v_mfma_f32_16x16x32_bf16 v[40:43], v[146:149], v[190:193], v[40:43]
	v_mfma_f32_16x16x32_bf16 v[28:31], v[138:141], v[198:201], v[28:31]
	v_mfma_f32_16x16x32_bf16 v[24:27], v[146:149], v[198:201], v[24:27]
	v_mfma_f32_16x16x32_bf16 v[12:15], v[138:141], v[212:215], v[12:15]
	v_mfma_f32_16x16x32_bf16 v[8:11], v[146:149], v[212:215], v[8:11]
	v_mfma_f32_16x16x32_bf16 v[60:63], v[142:145], v[186:189], v[60:63]
	v_mfma_f32_16x16x32_bf16 v[56:59], v[150:153], v[186:189], v[56:59]
	v_mfma_f32_16x16x32_bf16 v[44:47], v[142:145], v[194:197], v[44:47]
	v_mfma_f32_16x16x32_bf16 v[40:43], v[150:153], v[194:197], v[40:43]
	v_mfma_f32_16x16x32_bf16 v[28:31], v[142:145], v[208:211], v[28:31]
	v_mfma_f32_16x16x32_bf16 v[24:27], v[150:153], v[208:211], v[24:27]
	v_mfma_f32_16x16x32_bf16 v[12:15], v[142:145], v[216:219], v[12:15]
	v_mfma_f32_16x16x32_bf16 v[8:11], v[150:153], v[216:219], v[8:11]
	s_setprio 0
	s_setprio 1
	v_mfma_f32_16x16x32_bf16 v[52:55], v[154:157], v[182:185], v[52:55]
	v_mfma_f32_16x16x32_bf16 v[48:51], v[174:177], v[182:185], v[48:51]
	v_mfma_f32_16x16x32_bf16 v[36:39], v[154:157], v[190:193], v[36:39]
	v_mfma_f32_16x16x32_bf16 v[32:35], v[174:177], v[190:193], v[32:35]
	v_mfma_f32_16x16x32_bf16 v[20:23], v[154:157], v[198:201], v[20:23]
	v_mfma_f32_16x16x32_bf16 v[16:19], v[174:177], v[198:201], v[16:19]
	v_mfma_f32_16x16x32_bf16 v[4:7], v[154:157], v[212:215], v[4:7]
	v_mfma_f32_16x16x32_bf16 v[0:3], v[174:177], v[212:215], v[0:3]
	v_mfma_f32_16x16x32_bf16 v[52:55], v[170:173], v[186:189], v[52:55]
	v_mfma_f32_16x16x32_bf16 v[48:51], v[178:181], v[186:189], v[48:51]
	v_mfma_f32_16x16x32_bf16 v[36:39], v[170:173], v[194:197], v[36:39]
	v_mfma_f32_16x16x32_bf16 v[32:35], v[178:181], v[194:197], v[32:35]
	v_mfma_f32_16x16x32_bf16 v[20:23], v[170:173], v[208:211], v[20:23]
	v_mfma_f32_16x16x32_bf16 v[16:19], v[178:181], v[208:211], v[16:19]
	v_mfma_f32_16x16x32_bf16 v[4:7], v[170:173], v[216:219], v[4:7]
	v_mfma_f32_16x16x32_bf16 v[0:3], v[178:181], v[216:219], v[0:3]
	s_setprio 0
	s_barrier
	s_add_i32 s89, s89, 2
	s_add_u32 s18, s18, 0x100
	s_addc_u32 s19, s19, 0
	s_add_u32 s86, s86, 0x100
	s_addc_u32 s88, s88, 0
	s_cmp_gt_u32 s89, 13
	s_cbranch_scc0 .LBB0_517
	s_and_b64 vcc, exec, s[8:9]
	s_cbranch_vccz .LBB0_520
	s_barrier

.LBB0_715:
	s_lshl_b32 s86, s90, 15
	s_lshl_b64 s[6:7], s[86:87], 2
	v_readlane_b32 s5, v253, 48
	v_lshrrev_b32_e32 v16, 1, v10
	s_add_u32 s31, s5, s6
	v_readlane_b32 s5, v253, 49
	v_and_b32_e32 v16, 24, v16
	v_readlane_b32 s18, v254, 40
	s_addc_u32 s34, s5, s7
	v_and_b32_e32 v11, 15, v10
	v_lshlrev_b32_e32 v17, 1, v16
	v_lshlrev_b32_e32 v10, 2, v10
	s_lshl_b32 s3, s3, 5
	v_mov_b32_e32 v149, v161
	v_readlane_b32 s19, v254, 41
	v_lshl_or_b32 v156, s4, 6, v11
	v_lshl_or_b32 v11, v11, 6, v17
	s_lshl_b32 s4, s4, 13
	v_and_b32_e32 v10, 32, v10
	s_and_b32 s3, s3, 0x60
	s_add_i32 m0, s27, 0x18000
	v_lshl_add_u64 v[0:1], v[0:1], 0, s[38:39]
	v_lshl_add_u64 v[12:13], s[18:19], 0, v[148:149]
	v_mov_b32_e32 v147, v161
	v_bitop3_b32 v17, v11, s4, v10 bitop3:0xde
	s_lshl_b32 s4, s3, 7
	global_load_lds_dwordx4 v[0:1], off
	v_lshl_add_u64 v[0:1], v[2:3], 0, s[38:39]
	s_add_i32 m0, s27, 0x1a000
	s_add_i32 s35, s27, 0x8000
	s_add_i32 s84, s27, 0xa000
	v_lshl_add_u64 v[14:15], s[18:19], 0, v[146:147]
	v_bitop3_b32 v157, v11, s4, v10 bitop3:0xde
	global_load_lds_dwordx4 v[0:1], off
	v_lshl_add_u64 v[0:1], v[12:13], 0, s[38:39]
	s_mov_b32 m0, s35
	s_add_u32 s4, s20, 0x40080
	global_load_lds_dwordx4 v[0:1], off
	v_lshl_add_u64 v[0:1], v[14:15], 0, s[38:39]
	s_mov_b32 m0, s84
	s_addc_u32 s5, s21, 0
	global_load_lds_dwordx4 v[0:1], off
	s_add_i32 m0, s27, 0x1c000
	v_lshl_add_u64 v[0:1], s[4:5], 0, v[160:161]
	global_load_lds_dwordx4 v[0:1], off
	v_lshl_add_u64 v[0:1], s[4:5], 0, v[144:145]
	s_add_i32 m0, s27, 0x1e000
	s_cmpk_lt_u32 s2, 0x100
	global_load_lds_dwordx4 v[0:1], off
	s_waitcnt vmcnt(8)
	s_barrier
	v_lshlrev_b32_e32 v0, 14, v8
	v_and_b32_e32 v0, 0xffff8000, v0
	v_lshl_add_u32 v0, v7, 11, v0
	v_and_b32_e32 v1, 1, v8
	v_lshl_or_b32 v0, v1, 6, v0
	v_lshl_add_u32 v150, v9, 1, v0
	v_lshlrev_b32_e32 v0, 14, v4
	v_and_b32_e32 v0, 0xffff8000, v0
	s_waitcnt vmcnt(6)
	v_lshl_add_u32 v0, v5, 11, v0
	v_and_b32_e32 v1, 1, v4
	v_lshl_or_b32 v0, v1, 6, v0
	v_readlane_b32 s4, v254, 38
	s_cselect_b64 s[6:7], -1, 0
	v_or_b32_e32 v158, s3, v16
	v_mov_b32_e32 v151, v161
	v_lshl_add_u32 v152, v6, 1, v0
	v_mov_b32_e32 v153, v161
	s_mov_b32 s85, 0
	v_add_u32_e32 v159, 0, v17
	v_readlane_b32 s3, v254, 35
	s_mov_b32 s2, s4
	s_barrier
	v_readlane_b32 s5, v254, 39
	s_mov_b32 s99, 0
	s_branch .LBB0_718

.LBB0_717:
	s_mov_b32 s99, 1
	s_andn2_b64 vcc, exec, s[18:19]
	s_mov_b32 s3, s8
	s_mov_b32 s2, s10
	s_mov_b64 s[20:21], s[16:17]
	s_mov_b64 s[18:19], s[14:15]
	s_cbranch_vccz .LBB0_731

.LBB0_725:
	s_add_u32 s20, s18, 0xfffc0080
	s_addc_u32 s21, s19, -1
	s_add_i32 s78, 0, 0x10000
	s_cmp_eq_u32 s89, 12
	s_cselect_b32 s23, s11, s21
	s_cselect_b32 s22, s56, s20
	s_cselect_b32 s21, s9, s88
	s_cselect_b32 s20, s65, s86
	s_add_i32 s80, 0, 0x14000
	v_add_u32_e32 v44, s78, v157
	v_add_u32_e32 v154, s80, v157
	ds_read_b128 v[32:35], v44
	ds_read_b128 v[36:39], v44 offset:1024
	ds_read_b128 v[40:43], v44 offset:2048
	ds_read_b128 v[44:47], v44 offset:3072
	ds_read_b128 v[166:169], v154
	ds_read_b128 v[170:173], v154 offset:1024
	ds_read_b128 v[174:177], v154 offset:2048
	ds_read_b128 v[178:181], v154 offset:3072
	v_lshl_add_u64 v[154:155], s[18:19], 0, v[150:151]
	s_add_i32 m0, s27, 0xc000
	ds_read_b128 v[182:185], v159
	ds_read_b128 v[186:189], v159 offset:1024
	ds_read_b128 v[190:193], v159 offset:2048
	ds_read_b128 v[194:197], v159 offset:3072
	ds_read_b128 v[198:201], v159 offset:4096
	ds_read_b128 v[208:211], v159 offset:5120
	ds_read_b128 v[212:215], v159 offset:6144
	ds_read_b128 v[216:219], v159 offset:7168
	global_load_lds_dwordx4 v[154:155], off
	v_lshl_add_u64 v[154:155], s[18:19], 0, v[152:153]
	s_add_i32 m0, s27, 0xe000
	s_nop 0
	global_load_lds_dwordx4 v[154:155], off
	s_cmp_eq_u32 s99, 1
	s_cbranch_scc1 .Lskipw_p6_0
	s_waitcnt vmcnt(8)
.Lskipw_p6_0:
	s_waitcnt lgkmcnt(0)
	s_barrier
	s_setprio 1
	s_waitcnt lgkmcnt(0)
	v_mfma_f32_16x16x32_bf16 v[140:143], v[32:35], v[182:185], v[140:143]
	v_mfma_f32_16x16x32_bf16 v[136:139], v[40:43], v[182:185], v[136:139]
	v_mfma_f32_16x16x32_bf16 v[124:127], v[32:35], v[190:193], v[124:127]
	v_mfma_f32_16x16x32_bf16 v[120:123], v[40:43], v[190:193], v[120:123]
	v_mfma_f32_16x16x32_bf16 v[108:111], v[32:35], v[198:201], v[108:111]
	v_mfma_f32_16x16x32_bf16 v[104:107], v[40:43], v[198:201], v[104:107]
	v_mfma_f32_16x16x32_bf16 v[92:95], v[32:35], v[212:215], v[92:95]
	v_mfma_f32_16x16x32_bf16 v[88:91], v[40:43], v[212:215], v[88:91]
	v_mfma_f32_16x16x32_bf16 v[140:143], v[36:39], v[186:189], v[140:143]
	v_mfma_f32_16x16x32_bf16 v[136:139], v[44:47], v[186:189], v[136:139]
	v_mfma_f32_16x16x32_bf16 v[124:127], v[36:39], v[194:197], v[124:127]
	v_mfma_f32_16x16x32_bf16 v[120:123], v[44:47], v[194:197], v[120:123]
	v_mfma_f32_16x16x32_bf16 v[108:111], v[36:39], v[208:211], v[108:111]
	v_mfma_f32_16x16x32_bf16 v[104:107], v[44:47], v[208:211], v[104:107]
	v_mfma_f32_16x16x32_bf16 v[92:95], v[36:39], v[216:219], v[92:95]
	v_mfma_f32_16x16x32_bf16 v[88:91], v[44:47], v[216:219], v[88:91]
	s_setprio 0
	s_setprio 1
	v_mfma_f32_16x16x32_bf16 v[132:135], v[166:169], v[182:185], v[132:135]
	v_mfma_f32_16x16x32_bf16 v[128:131], v[174:177], v[182:185], v[128:131]
	v_mfma_f32_16x16x32_bf16 v[116:119], v[166:169], v[190:193], v[116:119]
	v_mfma_f32_16x16x32_bf16 v[112:115], v[174:177], v[190:193], v[112:115]
	v_mfma_f32_16x16x32_bf16 v[100:103], v[166:169], v[198:201], v[100:103]
	v_mfma_f32_16x16x32_bf16 v[96:99], v[174:177], v[198:201], v[96:99]
	v_mfma_f32_16x16x32_bf16 v[84:87], v[166:169], v[212:215], v[84:87]
	v_mfma_f32_16x16x32_bf16 v[80:83], v[174:177], v[212:215], v[80:83]
	v_mfma_f32_16x16x32_bf16 v[132:135], v[170:173], v[186:189], v[132:135]
	v_mfma_f32_16x16x32_bf16 v[128:131], v[178:181], v[186:189], v[128:131]
	v_mfma_f32_16x16x32_bf16 v[116:119], v[170:173], v[194:197], v[116:119]
	v_mfma_f32_16x16x32_bf16 v[112:115], v[178:181], v[194:197], v[112:115]
	v_mfma_f32_16x16x32_bf16 v[100:103], v[170:173], v[208:211], v[100:103]
	v_mfma_f32_16x16x32_bf16 v[96:99], v[178:181], v[208:211], v[96:99]
	v_mfma_f32_16x16x32_bf16 v[84:87], v[170:173], v[216:219], v[84:87]
	v_mfma_f32_16x16x32_bf16 v[80:83], v[178:181], v[216:219], v[80:83]
	s_setprio 0
	s_barrier
	s_add_i32 s78, s78, s26
	v_lshl_add_u64 v[154:155], s[20:21], 0, v[160:161]
	s_mov_b32 m0, s78
	ds_read_b128 v[182:185], v159 offset:16384
	ds_read_b128 v[186:189], v159 offset:17408
	ds_read_b128 v[190:193], v159 offset:18432
	ds_read_b128 v[194:197], v159 offset:19456
	ds_read_b128 v[198:201], v159 offset:20480
	ds_read_b128 v[208:211], v159 offset:21504
	ds_read_b128 v[212:215], v159 offset:22528
	ds_read_b128 v[216:219], v159 offset:23552
	global_load_lds_dwordx4 v[154:155], off
	s_add_i32 m0, s78, 0x2000
	s_add_u32 s78, s20, 0x40000
	v_lshl_add_u64 v[162:163], s[20:21], 0, v[144:145]
	s_addc_u32 s79, s21, 0
	s_add_i32 s80, s80, s26
	global_load_lds_dwordx4 v[162:163], off
	v_lshl_add_u64 v[202:203], s[78:79], 0, v[160:161]
	s_mov_b32 m0, s80
	v_lshl_add_u64 v[206:207], s[22:23], 0, v[146:147]
	global_load_lds_dwordx4 v[202:203], off
	v_lshl_add_u64 v[202:203], s[78:79], 0, v[144:145]
	s_add_i32 m0, s80, 0x2000
	s_nop 0
	global_load_lds_dwordx4 v[202:203], off
	v_lshl_add_u64 v[202:203], s[22:23], 0, v[148:149]
	s_mov_b32 m0, s27
	s_nop 0
	global_load_lds_dwordx4 v[202:203], off
	s_mov_b32 m0, s28
	s_nop 0
	global_load_lds_dwordx4 v[206:207], off
	s_cmp_eq_u32 s99, 1
	s_cbranch_scc1 .Lskipw_p6_1
	s_waitcnt vmcnt(8)
.Lskipw_p6_1:
	s_mov_b32 s99, 0
	s_waitcnt lgkmcnt(0)
	s_barrier
	s_setprio 1
	s_waitcnt lgkmcnt(0)
	v_mfma_f32_16x16x32_bf16 v[76:79], v[32:35], v[182:185], v[76:79]
	v_mfma_f32_16x16x32_bf16 v[72:75], v[40:43], v[182:185], v[72:75]
	v_mfma_f32_16x16x32_bf16 v[60:63], v[32:35], v[190:193], v[60:63]
	v_mfma_f32_16x16x32_bf16 v[56:59], v[40:43], v[190:193], v[56:59]
	v_mfma_f32_16x16x32_bf16 v[28:31], v[32:35], v[198:201], v[28:31]
	v_mfma_f32_16x16x32_bf16 v[24:27], v[40:43], v[198:201], v[24:27]
	v_mfma_f32_16x16x32_bf16 v[12:15], v[32:35], v[212:215], v[12:15]
	v_mfma_f32_16x16x32_bf16 v[8:11], v[40:43], v[212:215], v[8:11]
	v_mfma_f32_16x16x32_bf16 v[76:79], v[36:39], v[186:189], v[76:79]
	v_mfma_f32_16x16x32_bf16 v[72:75], v[44:47], v[186:189], v[72:75]
	v_mfma_f32_16x16x32_bf16 v[60:63], v[36:39], v[194:197], v[60:63]
	v_mfma_f32_16x16x32_bf16 v[56:59], v[44:47], v[194:197], v[56:59]
	v_mfma_f32_16x16x32_bf16 v[28:31], v[36:39], v[208:211], v[28:31]
	v_mfma_f32_16x16x32_bf16 v[24:27], v[44:47], v[208:211], v[24:27]
	v_mfma_f32_16x16x32_bf16 v[12:15], v[36:39], v[216:219], v[12:15]
	v_mfma_f32_16x16x32_bf16 v[8:11], v[44:47], v[216:219], v[8:11]
	s_setprio 0
	s_setprio 1
	v_mfma_f32_16x16x32_bf16 v[20:23], v[166:169], v[198:201], v[20:23]
	v_mfma_f32_16x16x32_bf16 v[16:19], v[174:177], v[198:201], v[16:19]
	v_mfma_f32_16x16x32_bf16 v[4:7], v[166:169], v[212:215], v[4:7]
	v_mfma_f32_16x16x32_bf16 v[0:3], v[174:177], v[212:215], v[0:3]
	v_mfma_f32_16x16x32_bf16 v[32:35], v[166:169], v[182:185], v[68:71]
	v_mfma_f32_16x16x32_bf16 v[36:39], v[174:177], v[182:185], v[64:67]
	v_mfma_f32_16x16x32_bf16 v[40:43], v[166:169], v[190:193], v[52:55]
	v_mfma_f32_16x16x32_bf16 v[44:47], v[174:177], v[190:193], v[48:51]
	v_mfma_f32_16x16x32_bf16 v[20:23], v[170:173], v[208:211], v[20:23]
	v_mfma_f32_16x16x32_bf16 v[16:19], v[178:181], v[208:211], v[16:19]
	v_mfma_f32_16x16x32_bf16 v[4:7], v[170:173], v[216:219], v[4:7]
	v_mfma_f32_16x16x32_bf16 v[0:3], v[178:181], v[216:219], v[0:3]
	v_mfma_f32_16x16x32_bf16 v[32:35], v[170:173], v[186:189], v[32:35]
	v_mfma_f32_16x16x32_bf16 v[36:39], v[178:181], v[186:189], v[36:39]
	v_mfma_f32_16x16x32_bf16 v[40:43], v[170:173], v[194:197], v[40:43]
	v_mfma_f32_16x16x32_bf16 v[44:47], v[178:181], v[194:197], v[44:47]
	s_setprio 0
	s_barrier
	s_add_i32 s78, 0, 0x18000
	s_add_i32 s79, 0, 0x1c000
	v_add_u32_e32 v68, s78, v157
	v_add_u32_e32 v178, s79, v157
	ds_read_b128 v[48:51], v68
	ds_read_b128 v[52:55], v68 offset:1024
	ds_read_b128 v[64:67], v68 offset:2048
	ds_read_b128 v[68:71], v68 offset:3072
	ds_read_b128 v[166:169], v178
	ds_read_b128 v[170:173], v178 offset:1024
	ds_read_b128 v[174:177], v178 offset:2048
	ds_read_b128 v[178:181], v178 offset:3072
	s_add_u32 s22, s22, 0x40000
	s_addc_u32 s23, s23, 0
	s_mov_b32 m0, s29
	v_lshl_add_u64 v[220:221], s[22:23], 0, v[148:149]
	ds_read_b128 v[182:185], v159 offset:32768
	ds_read_b128 v[186:189], v159 offset:33792
	ds_read_b128 v[190:193], v159 offset:34816
	ds_read_b128 v[194:197], v159 offset:35840
	ds_read_b128 v[198:201], v159 offset:36864
	ds_read_b128 v[208:211], v159 offset:37888
	ds_read_b128 v[212:215], v159 offset:38912
	ds_read_b128 v[216:219], v159 offset:39936
	global_load_lds_dwordx4 v[220:221], off
	v_lshl_add_u64 v[220:221], s[22:23], 0, v[146:147]
	s_mov_b32 m0, s30
	s_nop 0
	global_load_lds_dwordx4 v[220:221], off
	s_waitcnt vmcnt(8)
	s_waitcnt lgkmcnt(0)
	s_barrier
	s_setprio 1
	s_waitcnt lgkmcnt(0)
	v_mfma_f32_16x16x32_bf16 v[140:143], v[48:51], v[182:185], v[140:143]
	v_mfma_f32_16x16x32_bf16 v[136:139], v[64:67], v[182:185], v[136:139]
	v_mfma_f32_16x16x32_bf16 v[124:127], v[48:51], v[190:193], v[124:127]
	v_mfma_f32_16x16x32_bf16 v[120:123], v[64:67], v[190:193], v[120:123]
	v_mfma_f32_16x16x32_bf16 v[108:111], v[48:51], v[198:201], v[108:111]
	v_mfma_f32_16x16x32_bf16 v[104:107], v[64:67], v[198:201], v[104:107]
	v_mfma_f32_16x16x32_bf16 v[92:95], v[48:51], v[212:215], v[92:95]
	v_mfma_f32_16x16x32_bf16 v[88:91], v[64:67], v[212:215], v[88:91]
	v_mfma_f32_16x16x32_bf16 v[140:143], v[52:55], v[186:189], v[140:143]
	v_mfma_f32_16x16x32_bf16 v[136:139], v[68:71], v[186:189], v[136:139]
	v_mfma_f32_16x16x32_bf16 v[124:127], v[52:55], v[194:197], v[124:127]
	v_mfma_f32_16x16x32_bf16 v[120:123], v[68:71], v[194:197], v[120:123]
	v_mfma_f32_16x16x32_bf16 v[108:111], v[52:55], v[208:211], v[108:111]
	v_mfma_f32_16x16x32_bf16 v[104:107], v[68:71], v[208:211], v[104:107]
	v_mfma_f32_16x16x32_bf16 v[92:95], v[52:55], v[216:219], v[92:95]
	v_mfma_f32_16x16x32_bf16 v[88:91], v[68:71], v[216:219], v[88:91]
	s_setprio 0
	s_setprio 1
	v_mfma_f32_16x16x32_bf16 v[132:135], v[166:169], v[182:185], v[132:135]
	v_mfma_f32_16x16x32_bf16 v[128:131], v[174:177], v[182:185], v[128:131]
	v_mfma_f32_16x16x32_bf16 v[116:119], v[166:169], v[190:193], v[116:119]
	v_mfma_f32_16x16x32_bf16 v[112:115], v[174:177], v[190:193], v[112:115]
	v_mfma_f32_16x16x32_bf16 v[100:103], v[166:169], v[198:201], v[100:103]
	v_mfma_f32_16x16x32_bf16 v[96:99], v[174:177], v[198:201], v[96:99]
	v_mfma_f32_16x16x32_bf16 v[84:87], v[166:169], v[212:215], v[84:87]
	v_mfma_f32_16x16x32_bf16 v[80:83], v[174:177], v[212:215], v[80:83]
	v_mfma_f32_16x16x32_bf16 v[132:135], v[170:173], v[186:189], v[132:135]
	v_mfma_f32_16x16x32_bf16 v[128:131], v[178:181], v[186:189], v[128:131]
	v_mfma_f32_16x16x32_bf16 v[116:119], v[170:173], v[194:197], v[116:119]
	v_mfma_f32_16x16x32_bf16 v[112:115], v[178:181], v[194:197], v[112:115]
	v_mfma_f32_16x16x32_bf16 v[100:103], v[170:173], v[208:211], v[100:103]
	v_mfma_f32_16x16x32_bf16 v[96:99], v[178:181], v[208:211], v[96:99]
	v_mfma_f32_16x16x32_bf16 v[84:87], v[170:173], v[216:219], v[84:87]
	v_mfma_f32_16x16x32_bf16 v[80:83], v[178:181], v[216:219], v[80:83]
	s_setprio 0
	s_barrier
	s_add_i32 s22, s78, s26
	v_lshl_add_u64 v[154:155], v[154:155], 0, s[38:39]
	s_mov_b32 m0, s22
	ds_read_b128 v[182:185], v159 offset:49152
	ds_read_b128 v[186:189], v159 offset:50176
	ds_read_b128 v[190:193], v159 offset:51200
	ds_read_b128 v[194:197], v159 offset:52224
	ds_read_b128 v[198:201], v159 offset:53248
	ds_read_b128 v[208:211], v159 offset:54272
	ds_read_b128 v[212:215], v159 offset:55296
	ds_read_b128 v[216:219], v159 offset:56320
	global_load_lds_dwordx4 v[154:155], off
	s_add_i32 m0, s22, 0x2000
	s_add_u32 s20, s20, 0x40080
	v_lshl_add_u64 v[154:155], v[162:163], 0, s[38:39]
	s_addc_u32 s21, s21, 0
	s_add_i32 s22, s79, s26
	global_load_lds_dwordx4 v[154:155], off
	v_lshl_add_u64 v[154:155], s[20:21], 0, v[160:161]
	s_mov_b32 m0, s22
	s_nop 0
	global_load_lds_dwordx4 v[154:155], off
	v_lshl_add_u64 v[154:155], s[20:21], 0, v[144:145]
	s_add_i32 m0, s22, 0x2000
	s_nop 0
	global_load_lds_dwordx4 v[154:155], off
	v_lshl_add_u64 v[154:155], v[202:203], 0, s[38:39]
	s_mov_b32 m0, s35
	s_nop 0
	global_load_lds_dwordx4 v[154:155], off
	v_lshl_add_u64 v[154:155], v[206:207], 0, s[38:39]
	s_mov_b32 m0, s84
	s_nop 0
	global_load_lds_dwordx4 v[154:155], off
	s_waitcnt vmcnt(8)
	s_waitcnt lgkmcnt(0)
	s_barrier
	s_setprio 1
	s_waitcnt lgkmcnt(0)
	v_mfma_f32_16x16x32_bf16 v[76:79], v[48:51], v[182:185], v[76:79]
	v_mfma_f32_16x16x32_bf16 v[72:75], v[64:67], v[182:185], v[72:75]
	v_mfma_f32_16x16x32_bf16 v[60:63], v[48:51], v[190:193], v[60:63]
	v_mfma_f32_16x16x32_bf16 v[56:59], v[64:67], v[190:193], v[56:59]
	v_mfma_f32_16x16x32_bf16 v[28:31], v[48:51], v[198:201], v[28:31]
	v_mfma_f32_16x16x32_bf16 v[24:27], v[64:67], v[198:201], v[24:27]
	v_mfma_f32_16x16x32_bf16 v[12:15], v[48:51], v[212:215], v[12:15]
	v_mfma_f32_16x16x32_bf16 v[8:11], v[64:67], v[212:215], v[8:11]
	v_mfma_f32_16x16x32_bf16 v[76:79], v[52:55], v[186:189], v[76:79]
	v_mfma_f32_16x16x32_bf16 v[72:75], v[68:71], v[186:189], v[72:75]
	v_mfma_f32_16x16x32_bf16 v[60:63], v[52:55], v[194:197], v[60:63]
	v_mfma_f32_16x16x32_bf16 v[56:59], v[68:71], v[194:197], v[56:59]
	v_mfma_f32_16x16x32_bf16 v[28:31], v[52:55], v[208:211], v[28:31]
	v_mfma_f32_16x16x32_bf16 v[24:27], v[68:71], v[208:211], v[24:27]
	v_mfma_f32_16x16x32_bf16 v[12:15], v[52:55], v[216:219], v[12:15]
	v_mfma_f32_16x16x32_bf16 v[8:11], v[68:71], v[216:219], v[8:11]
	s_setprio 0
	s_setprio 1
	v_mfma_f32_16x16x32_bf16 v[32:35], v[166:169], v[182:185], v[32:35]
	v_mfma_f32_16x16x32_bf16 v[68:71], v[170:173], v[186:189], v[32:35]
	v_mfma_f32_16x16x32_bf16 v[32:35], v[174:177], v[182:185], v[36:39]
	v_mfma_f32_16x16x32_bf16 v[64:67], v[178:181], v[186:189], v[32:35]
	v_mfma_f32_16x16x32_bf16 v[32:35], v[166:169], v[190:193], v[40:43]
	v_mfma_f32_16x16x32_bf16 v[52:55], v[170:173], v[194:197], v[32:35]
	v_mfma_f32_16x16x32_bf16 v[32:35], v[174:177], v[190:193], v[44:47]
	v_mfma_f32_16x16x32_bf16 v[20:23], v[166:169], v[198:201], v[20:23]
	v_mfma_f32_16x16x32_bf16 v[16:19], v[174:177], v[198:201], v[16:19]
	v_mfma_f32_16x16x32_bf16 v[4:7], v[166:169], v[212:215], v[4:7]
	v_mfma_f32_16x16x32_bf16 v[0:3], v[174:177], v[212:215], v[0:3]
	v_mfma_f32_16x16x32_bf16 v[48:51], v[178:181], v[194:197], v[32:35]
	v_mfma_f32_16x16x32_bf16 v[20:23], v[170:173], v[208:211], v[20:23]
	v_mfma_f32_16x16x32_bf16 v[16:19], v[178:181], v[208:211], v[16:19]
	v_mfma_f32_16x16x32_bf16 v[4:7], v[170:173], v[216:219], v[4:7]
	v_mfma_f32_16x16x32_bf16 v[0:3], v[178:181], v[216:219], v[0:3]
	s_setprio 0
	s_barrier
	s_add_i32 s89, s89, 2
	s_add_u32 s18, s18, 0x100
	s_addc_u32 s19, s19, 0
	s_add_u32 s86, s86, 0x100
	s_addc_u32 s88, s88, 0
	s_cmp_gt_u32 s89, 13
	s_cbranch_scc0 .LBB0_725
	s_and_b64 vcc, exec, s[6:7]
	s_cbranch_vccz .LBB0_728
	s_barrier
